# removes 128 dead zero-init v_mov before full-row row_ror DPP moves in the up-GEMM conv epilogue (instruction selection)
# speedup vs baseline: 1.0081x; 1.0081x over previous
; DI u32x4 pack8(const float (&f)[8]) { u32x4 w; w.x = pk2(f[0], f[1]); w.y = pk2(f[2], f[3]); w.z = pk2(f[4], f[5]); w.w = pk2(f[6], f[7]); return w; }
; DI float fsilu(float x) { return x * fsigmoid(x); }
; DI float dpp_ror1(float v) { return __int_as_float(__builtin_amdgcn_update_dpp(0, __float_as_int(v), 0x121, 0xf, 0xf, false)); }
; DI float dpp_ror2(float v) { return __int_as_float(__builtin_amdgcn_update_dpp(0, __float_as_int(v), 0x122, 0xf, 0xf, false)); }
;     DI void operator()(const f32x4 (&acc)[2][2][4][2], const pg8::Unit& u, int wr, int wcv, int fr, int fq) const {
;     ...
;             for (int m = 0; m < 4; ++m) {
;                 const int lrow = 64 * blk + 16 * m + fr, t = 254 * u.pm - 2 + lrow, spos = t & 2047;
;                 float o[8], r1[8], r2[8];
; #pragma unroll
;                 for (int e = 0; e < 8; ++e) { const float uc = acc[ai][0][m][e >> 2][e & 3], gv = acc[ai][1][m][e >> 2][e & 3];
;                     r1[e] = dpp_ror1(uc); r2[e] = dpp_ror2(uc);
;                     float um1 = (fr >= 1) ? r1[e] : p1[e], um2 = (fr >= 2) ? r2[e] : p2[e];
;                     if (spos < 1) um1 = 0.f;
;                     if (spos < 2) um2 = 0.f;
;                     const float v = bb[e] + w0[e] * um2 + w1[e] * um1 + w2[e] * uc;
;                     o[e] = fsilu(v) * gv; }
; #pragma unroll
;                 for (int e = 0; e < 8; ++e) { p1[e] = r1[e]; p2[e] = r2[e]; }
;                 if (lrow >= 2 && t < T) *(u32x4*)(act + (size_t)t * DFF + ch0) = pack8(o);
;             }
.LBB0_883:
	s_waitcnt vmcnt(0)
	s_mul_i32 s53, s87, 0xfe
	s_add_i32 s53, s53, -2
	v_add_u32_e32 v239, s53, v180
	v_cmp_gt_i32_e32 vcc, s19, v239
	v_mov_b32_dpp v235, v156 row_ror:1 row_mask:0xf bank_mask:0xf
	v_mov_b32_dpp v234, v156 row_ror:2 row_mask:0xf bank_mask:0xf
	v_mov_b32_dpp v232, v157 row_ror:1 row_mask:0xf bank_mask:0xf
	v_mov_b32_dpp v223, v157 row_ror:2 row_mask:0xf bank_mask:0xf
	v_mov_b32_dpp v222, v158 row_ror:1 row_mask:0xf bank_mask:0xf
	v_mov_b32_dpp v221, v158 row_ror:2 row_mask:0xf bank_mask:0xf
	v_mov_b32_dpp v220, v159 row_ror:1 row_mask:0xf bank_mask:0xf
	v_mov_b32_dpp v219, v159 row_ror:2 row_mask:0xf bank_mask:0xf
	v_mov_b32_dpp v218, v148 row_ror:1 row_mask:0xf bank_mask:0xf
	v_mov_b32_dpp v217, v148 row_ror:2 row_mask:0xf bank_mask:0xf
	v_mov_b32_dpp v216, v149 row_ror:1 row_mask:0xf bank_mask:0xf
	v_mov_b32_dpp v215, v149 row_ror:2 row_mask:0xf bank_mask:0xf
	v_mov_b32_dpp v214, v150 row_ror:1 row_mask:0xf bank_mask:0xf
	v_mov_b32_dpp v213, v150 row_ror:2 row_mask:0xf bank_mask:0xf
	v_mov_b32_dpp v212, v151 row_ror:1 row_mask:0xf bank_mask:0xf
	v_mov_b32_dpp v195, v151 row_ror:2 row_mask:0xf bank_mask:0xf
	s_and_b64 s[50:51], s[44:45], vcc
	s_and_saveexec_b64 s[58:59], s[50:51]
	s_cbranch_execz .LBB0_885
	v_and_b32_e32 v204, 0x7ff, v239
	v_cndmask_b32_e64 v164, v235, v164, s[40:41]
	v_cmp_eq_u32_e32 vcc, 0, v204
	v_mov_b32_e32 v202, v156
	v_cndmask_b32_e64 v156, v243, v234, s[42:43]
	v_cmp_gt_u32_e64 s[50:51], 2, v204
	v_cndmask_b32_e64 v201, v164, 0, vcc
	v_mov_b32_e32 v203, v84
	v_mov_b32_e32 v200, v88
	v_cndmask_b32_e64 v156, v156, 0, s[50:51]
	v_pk_mul_f32 v[200:201], v[202:203], v[200:201]
	v_fma_f32 v156, v80, v156, v92
	v_add_f32_e32 v156, v201, v156
	v_add_f32_e32 v200, v200, v156
	v_mul_f32_e32 v156, 0xbfb8aa3b, v200
	v_exp_f32_e32 v201, v156
	v_cndmask_b32_e64 v156, v232, v165, s[40:41]
	v_cndmask_b32_e64 v165, v156, 0, vcc
	v_mov_b32_e32 v156, v157
	v_mov_b32_e32 v157, v85
	v_mov_b32_e32 v164, v89
	v_pk_mul_f32 v[156:157], v[156:157], v[164:165]
	v_cndmask_b32_e64 v164, v242, v223, s[42:43]
	v_cndmask_b32_e64 v164, v164, 0, s[50:51]
	v_fma_f32 v164, v81, v164, v93
	v_add_f32_e32 v157, v157, v164
	v_add_f32_e32 v156, v156, v157
	v_mul_f32_e32 v157, 0xbfb8aa3b, v156
	v_exp_f32_e32 v157, v157
	v_add_f32_e32 v164, 1.0, v201
	v_rcp_f32_e32 v164, v164
	v_mov_b32_e32 v165, v86
	v_add_f32_e32 v157, 1.0, v157
	v_rcp_f32_e32 v157, v157
	v_mul_f32_e32 v164, v200, v164
	v_mul_f32_e32 v200, v152, v164
	v_mov_b32_e32 v164, v158
	v_mul_f32_e32 v152, v156, v157
	v_cndmask_b32_e64 v156, v222, v166, s[40:41]
	v_cndmask_b32_e64 v158, v240, v221, s[42:43]
	v_cndmask_b32_e64 v157, v156, 0, vcc
	v_mov_b32_e32 v156, v90
	v_cndmask_b32_e64 v158, v158, 0, s[50:51]
	v_pk_mul_f32 v[156:157], v[164:165], v[156:157]
	v_fma_f32 v158, v82, v158, v94
	v_add_f32_e32 v157, v157, v158
	v_add_f32_e32 v164, v156, v157
	v_mul_f32_e32 v156, 0xbfb8aa3b, v164
	v_exp_f32_e32 v165, v156
	v_cndmask_b32_e64 v156, v220, v167, s[40:41]
	v_cndmask_b32_e64 v157, v156, 0, vcc
	v_mov_b32_e32 v158, v159
	v_mov_b32_e32 v159, v87
	v_mov_b32_e32 v156, v91
	v_pk_mul_f32 v[156:157], v[158:159], v[156:157]
	v_cndmask_b32_e64 v158, v237, v219, s[42:43]
	v_cndmask_b32_e64 v158, v158, 0, s[50:51]
	v_fma_f32 v158, v83, v158, v95
	v_add_f32_e32 v157, v157, v158
	v_add_f32_e32 v158, v156, v157
	v_mul_f32_e32 v156, 0xbfb8aa3b, v158
	v_exp_f32_e32 v156, v156
	v_mul_f32_e32 v159, v153, v152
	v_add_f32_e32 v152, 1.0, v165
	v_rcp_f32_e32 v165, v152
	v_add_f32_e32 v152, 1.0, v156
	v_rcp_f32_e32 v166, v152
	v_cndmask_b32_e64 v152, v218, v160, s[40:41]
	v_mov_b32_e32 v156, v148
	v_cndmask_b32_e64 v148, v241, v217, s[42:43]
	v_cndmask_b32_e64 v153, v152, 0, vcc
	v_mov_b32_e32 v157, v64
	v_mov_b32_e32 v152, v68
	v_cndmask_b32_e64 v148, v148, 0, s[50:51]
	v_pk_mul_f32 v[152:153], v[156:157], v[152:153]
	v_fma_f32 v148, v60, v148, v72
	v_add_f32_e32 v148, v153, v148
	v_add_f32_e32 v156, v152, v148
	v_mul_f32_e32 v148, 0xbfb8aa3b, v156
	v_exp_f32_e32 v148, v148
	v_mul_f32_e32 v152, v164, v165
	v_mul_f32_e32 v157, v158, v166
	v_mul_f32_e32 v154, v154, v152
	v_add_f32_e32 v148, 1.0, v148
	v_rcp_f32_e32 v158, v148
	v_cndmask_b32_e64 v148, v216, v161, s[40:41]
	v_cndmask_b32_e64 v153, v148, 0, vcc
	v_mov_b32_e32 v148, v149
	v_mov_b32_e32 v149, v65
	v_mov_b32_e32 v152, v69
	v_pk_mul_f32 v[148:149], v[148:149], v[152:153]
	v_cndmask_b32_e64 v152, v238, v215, s[42:43]
	v_cndmask_b32_e64 v152, v152, 0, s[50:51]
	v_fma_f32 v152, v61, v152, v73
	v_add_f32_e32 v149, v149, v152
	v_add_f32_e32 v160, v148, v149
	v_mul_f32_e32 v148, 0xbfb8aa3b, v160
	v_exp_f32_e32 v148, v148
	v_mul_f32_e32 v149, v156, v158
	v_mul_f32_e32 v156, v144, v149
	v_mov_b32_e32 v152, v150
	v_add_f32_e32 v144, 1.0, v148
	v_cndmask_b32_e64 v148, v214, v162, s[40:41]
	v_cndmask_b32_e64 v150, v236, v213, s[42:43]
	v_cndmask_b32_e64 v149, v148, 0, vcc
	v_mov_b32_e32 v153, v66
	v_mov_b32_e32 v148, v70
	v_cndmask_b32_e64 v150, v150, 0, s[50:51]
	v_pk_mul_f32 v[148:149], v[152:153], v[148:149]
	v_fma_f32 v150, v62, v150, v74
	v_add_f32_e32 v149, v149, v150
	v_add_f32_e32 v152, v148, v149
	v_mul_f32_e32 v148, 0xbfb8aa3b, v152
	v_exp_f32_e32 v153, v148
	v_cndmask_b32_e64 v148, v212, v163, s[40:41]
	v_cndmask_b32_e64 v149, v148, 0, vcc
	v_mov_b32_e32 v150, v151
	v_mov_b32_e32 v151, v67
	v_mov_b32_e32 v148, v71
	v_pk_mul_f32 v[148:149], v[150:151], v[148:149]
	v_cndmask_b32_e64 v150, v233, v195, s[42:43]
	v_cndmask_b32_e64 v150, v150, 0, s[50:51]
	v_fma_f32 v150, v63, v150, v75
	v_add_f32_e32 v149, v149, v150
	v_add_f32_e32 v148, v148, v149
	v_mul_f32_e32 v149, 0xbfb8aa3b, v148
	v_exp_f32_e32 v149, v149
	v_rcp_f32_e32 v144, v144
	v_add_f32_e32 v150, 1.0, v153
	v_rcp_f32_e32 v150, v150
	v_add_f32_e32 v149, 1.0, v149
	v_rcp_f32_e32 v149, v149
	v_mul_f32_e32 v144, v160, v144
	v_mul_f32_e32 v151, v145, v144
	v_mul_f32_e32 v144, v152, v150
	v_mul_f32_e32 v150, v146, v144
	v_mul_f32_e32 v144, v148, v149
	v_mov_b64_e32 v[148:149], s[4:5]
	s_movk_i32 s50, 0x1600
	v_mul_f32_e32 v155, v155, v157
	v_mul_f32_e32 v147, v147, v144
	v_mad_i64_i32 v[148:149], s[50:51], v239, s50, v[148:149]
	v_cvt_pk_bf16_f32 v144, v200, v159
	v_cvt_pk_bf16_f32 v145, v154, v155
	v_cvt_pk_bf16_f32 v146, v156, v151
	v_cvt_pk_bf16_f32 v147, v150, v147
	v_lshl_add_u64 v[148:149], v[178:179], 1, v[148:149]
	global_store_dwordx4 v[148:149], v[144:147], off
; DI u32x4 pack8(const float (&f)[8]) { u32x4 w; w.x = pk2(f[0], f[1]); w.y = pk2(f[2], f[3]); w.z = pk2(f[4], f[5]); w.w = pk2(f[6], f[7]); return w; }
; DI float fsilu(float x) { return x * fsigmoid(x); }
; DI float dpp_ror1(float v) { return __int_as_float(__builtin_amdgcn_update_dpp(0, __float_as_int(v), 0x121, 0xf, 0xf, false)); }
; DI float dpp_ror2(float v) { return __int_as_float(__builtin_amdgcn_update_dpp(0, __float_as_int(v), 0x122, 0xf, 0xf, false)); }
;     DI void operator()(const f32x4 (&acc)[2][2][4][2], const pg8::Unit& u, int wr, int wcv, int fr, int fq) const {
;     ...
;             for (int m = 0; m < 4; ++m) {
;                 const int lrow = 64 * blk + 16 * m + fr, t = 254 * u.pm - 2 + lrow, spos = t & 2047;
;                 float o[8], r1[8], r2[8];
; #pragma unroll
;                 for (int e = 0; e < 8; ++e) { const float uc = acc[ai][0][m][e >> 2][e & 3], gv = acc[ai][1][m][e >> 2][e & 3];
;                     r1[e] = dpp_ror1(uc); r2[e] = dpp_ror2(uc);
;                     float um1 = (fr >= 1) ? r1[e] : p1[e], um2 = (fr >= 2) ? r2[e] : p2[e];
;                     if (spos < 1) um1 = 0.f;
;                     if (spos < 2) um2 = 0.f;
;                     const float v = bb[e] + w0[e] * um2 + w1[e] * um1 + w2[e] * uc;
;                     o[e] = fsilu(v) * gv; }
; #pragma unroll
;                 for (int e = 0; e < 8; ++e) { p1[e] = r1[e]; p2[e] = r2[e]; }
;                 if (lrow >= 2 && t < T) *(u32x4*)(act + (size_t)t * DFF + ch0) = pack8(o);
;             }
.LBB0_885:
	s_or_b64 exec, exec, s[58:59]
	v_add_u32_e32 v160, s53, v183
	v_cmp_gt_i32_e32 vcc, s19, v160
	v_mov_b32_dpp v159, v140 row_ror:1 row_mask:0xf bank_mask:0xf
	v_mov_b32_dpp v158, v140 row_ror:2 row_mask:0xf bank_mask:0xf
	v_mov_b32_dpp v157, v141 row_ror:1 row_mask:0xf bank_mask:0xf
	v_mov_b32_dpp v156, v141 row_ror:2 row_mask:0xf bank_mask:0xf
	v_mov_b32_dpp v155, v142 row_ror:1 row_mask:0xf bank_mask:0xf
	v_mov_b32_dpp v154, v142 row_ror:2 row_mask:0xf bank_mask:0xf
	v_mov_b32_dpp v153, v143 row_ror:1 row_mask:0xf bank_mask:0xf
	v_mov_b32_dpp v152, v143 row_ror:2 row_mask:0xf bank_mask:0xf
	v_mov_b32_dpp v151, v132 row_ror:1 row_mask:0xf bank_mask:0xf
	v_mov_b32_dpp v150, v132 row_ror:2 row_mask:0xf bank_mask:0xf
	v_mov_b32_dpp v149, v133 row_ror:1 row_mask:0xf bank_mask:0xf
	v_mov_b32_dpp v148, v133 row_ror:2 row_mask:0xf bank_mask:0xf
	v_mov_b32_dpp v147, v134 row_ror:1 row_mask:0xf bank_mask:0xf
	v_mov_b32_dpp v146, v134 row_ror:2 row_mask:0xf bank_mask:0xf
	v_mov_b32_dpp v145, v135 row_ror:1 row_mask:0xf bank_mask:0xf
	v_mov_b32_dpp v144, v135 row_ror:2 row_mask:0xf bank_mask:0xf
	s_and_b64 s[50:51], s[24:25], vcc
	s_and_saveexec_b64 s[58:59], s[50:51]
	s_cbranch_execz .LBB0_887
	v_and_b32_e32 v161, 0x7ff, v160
	v_cndmask_b32_e64 v162, v159, v235, s[40:41]
	v_cmp_eq_u32_e32 vcc, 0, v161
	v_mov_b32_e32 v164, v140
	v_cndmask_b32_e64 v140, v234, v158, s[42:43]
	v_cmp_gt_u32_e64 s[50:51], 2, v161
	v_cndmask_b32_e64 v163, v162, 0, vcc
	v_mov_b32_e32 v165, v84
	v_mov_b32_e32 v162, v88
	v_cndmask_b32_e64 v140, v140, 0, s[50:51]
	v_pk_mul_f32 v[162:163], v[164:165], v[162:163]
	v_fma_f32 v140, v80, v140, v92
	v_add_f32_e32 v140, v163, v140
	v_add_f32_e32 v161, v162, v140
	v_mul_f32_e32 v140, 0xbfb8aa3b, v161
	v_exp_f32_e32 v164, v140
	v_cndmask_b32_e64 v140, v157, v232, s[40:41]
	v_cndmask_b32_e64 v163, v140, 0, vcc
	v_mov_b32_e32 v140, v141
	v_mov_b32_e32 v141, v85
	v_mov_b32_e32 v162, v89
	v_pk_mul_f32 v[140:141], v[140:141], v[162:163]
	v_cndmask_b32_e64 v162, v223, v156, s[42:43]
	v_cndmask_b32_e64 v162, v162, 0, s[50:51]
	v_fma_f32 v162, v81, v162, v93
	v_add_f32_e32 v141, v141, v162
	v_add_f32_e32 v140, v140, v141
	v_mul_f32_e32 v141, 0xbfb8aa3b, v140
	v_exp_f32_e32 v141, v141
	v_add_f32_e32 v162, 1.0, v164
	v_rcp_f32_e32 v162, v162
	v_mov_b32_e32 v163, v86
	v_add_f32_e32 v141, 1.0, v141
	v_rcp_f32_e32 v141, v141
	v_mul_f32_e32 v161, v161, v162
	v_mul_f32_e32 v161, v136, v161
	v_mov_b32_e32 v162, v142
	v_mul_f32_e32 v136, v140, v141
	v_cndmask_b32_e64 v140, v155, v222, s[40:41]
	v_cndmask_b32_e64 v142, v221, v154, s[42:43]
	v_cndmask_b32_e64 v141, v140, 0, vcc
	v_mov_b32_e32 v140, v90
	v_cndmask_b32_e64 v142, v142, 0, s[50:51]
	v_pk_mul_f32 v[140:141], v[162:163], v[140:141]
	v_fma_f32 v142, v82, v142, v94
	v_add_f32_e32 v141, v141, v142
	v_add_f32_e32 v162, v140, v141
	v_mul_f32_e32 v140, 0xbfb8aa3b, v162
	v_exp_f32_e32 v163, v140
	v_cndmask_b32_e64 v140, v153, v220, s[40:41]
	v_cndmask_b32_e64 v141, v140, 0, vcc
	v_mov_b32_e32 v142, v143
	v_mov_b32_e32 v143, v87
	v_mov_b32_e32 v140, v91
	v_pk_mul_f32 v[140:141], v[142:143], v[140:141]
	v_cndmask_b32_e64 v142, v219, v152, s[42:43]
	v_cndmask_b32_e64 v142, v142, 0, s[50:51]
	v_fma_f32 v142, v83, v142, v95
	v_add_f32_e32 v141, v141, v142
	v_add_f32_e32 v142, v140, v141
	v_mul_f32_e32 v140, 0xbfb8aa3b, v142
	v_exp_f32_e32 v140, v140
	v_mul_f32_e32 v143, v137, v136
	v_add_f32_e32 v136, 1.0, v163
	v_rcp_f32_e32 v163, v136
	v_add_f32_e32 v136, 1.0, v140
	v_rcp_f32_e32 v164, v136
	v_cndmask_b32_e64 v136, v151, v218, s[40:41]
	v_mov_b32_e32 v140, v132
	v_cndmask_b32_e64 v132, v217, v150, s[42:43]
	v_cndmask_b32_e64 v137, v136, 0, vcc
	v_mov_b32_e32 v141, v64
	v_mov_b32_e32 v136, v68
	v_cndmask_b32_e64 v132, v132, 0, s[50:51]
	v_pk_mul_f32 v[136:137], v[140:141], v[136:137]
	v_fma_f32 v132, v60, v132, v72
	v_add_f32_e32 v132, v137, v132
	v_add_f32_e32 v140, v136, v132
	v_mul_f32_e32 v132, 0xbfb8aa3b, v140
	v_exp_f32_e32 v132, v132
	v_mul_f32_e32 v136, v162, v163
	v_mul_f32_e32 v141, v142, v164
	v_mul_f32_e32 v138, v138, v136
	v_add_f32_e32 v132, 1.0, v132
	v_rcp_f32_e32 v142, v132
	v_cndmask_b32_e64 v132, v149, v216, s[40:41]
	v_cndmask_b32_e64 v137, v132, 0, vcc
	v_mov_b32_e32 v132, v133
	v_mov_b32_e32 v133, v65
	v_mov_b32_e32 v136, v69
	v_pk_mul_f32 v[132:133], v[132:133], v[136:137]
	v_cndmask_b32_e64 v136, v215, v148, s[42:43]
	v_cndmask_b32_e64 v136, v136, 0, s[50:51]
	v_fma_f32 v136, v61, v136, v73
	v_add_f32_e32 v133, v133, v136
	v_add_f32_e32 v162, v132, v133
	v_mul_f32_e32 v132, 0xbfb8aa3b, v162
	v_exp_f32_e32 v132, v132
	v_mul_f32_e32 v133, v140, v142
	v_mul_f32_e32 v140, v128, v133
	v_mov_b32_e32 v136, v134
	v_add_f32_e32 v128, 1.0, v132
	v_cndmask_b32_e64 v132, v147, v214, s[40:41]
	v_cndmask_b32_e64 v134, v213, v146, s[42:43]
	v_cndmask_b32_e64 v133, v132, 0, vcc
	v_mov_b32_e32 v137, v66
	v_mov_b32_e32 v132, v70
	v_cndmask_b32_e64 v134, v134, 0, s[50:51]
	v_pk_mul_f32 v[132:133], v[136:137], v[132:133]
	v_fma_f32 v134, v62, v134, v74
	v_add_f32_e32 v133, v133, v134
	v_add_f32_e32 v136, v132, v133
	v_mul_f32_e32 v132, 0xbfb8aa3b, v136
	v_exp_f32_e32 v137, v132
	v_cndmask_b32_e64 v132, v145, v212, s[40:41]
	v_cndmask_b32_e64 v133, v132, 0, vcc
	v_mov_b32_e32 v134, v135
	v_mov_b32_e32 v135, v67
	v_mov_b32_e32 v132, v71
	v_pk_mul_f32 v[132:133], v[134:135], v[132:133]
	v_cndmask_b32_e64 v134, v195, v144, s[42:43]
	v_cndmask_b32_e64 v134, v134, 0, s[50:51]
	v_fma_f32 v134, v63, v134, v75
	v_add_f32_e32 v133, v133, v134
	v_add_f32_e32 v132, v132, v133
	v_mul_f32_e32 v133, 0xbfb8aa3b, v132
	v_exp_f32_e32 v133, v133
	v_rcp_f32_e32 v128, v128
	v_add_f32_e32 v134, 1.0, v137
	v_rcp_f32_e32 v134, v134
	v_add_f32_e32 v133, 1.0, v133
	v_rcp_f32_e32 v133, v133
	v_mul_f32_e32 v128, v162, v128
	v_mul_f32_e32 v135, v129, v128
	v_mul_f32_e32 v128, v136, v134
	v_mul_f32_e32 v134, v130, v128
	v_mul_f32_e32 v128, v132, v133
	v_mov_b64_e32 v[132:133], s[4:5]
	s_movk_i32 s50, 0x1600
	v_mul_f32_e32 v139, v139, v141
	v_mul_f32_e32 v131, v131, v128
	v_mad_i64_i32 v[132:133], s[50:51], v160, s50, v[132:133]
	v_cvt_pk_bf16_f32 v128, v161, v143
	v_cvt_pk_bf16_f32 v129, v138, v139
	v_cvt_pk_bf16_f32 v130, v140, v135
	v_cvt_pk_bf16_f32 v131, v134, v131
	v_lshl_add_u64 v[132:133], v[178:179], 1, v[132:133]
	global_store_dwordx4 v[132:133], v[128:131], off
; DI u32x4 pack8(const float (&f)[8]) { u32x4 w; w.x = pk2(f[0], f[1]); w.y = pk2(f[2], f[3]); w.z = pk2(f[4], f[5]); w.w = pk2(f[6], f[7]); return w; }
; DI float fsilu(float x) { return x * fsigmoid(x); }
; DI float dpp_ror1(float v) { return __int_as_float(__builtin_amdgcn_update_dpp(0, __float_as_int(v), 0x121, 0xf, 0xf, false)); }
; DI float dpp_ror2(float v) { return __int_as_float(__builtin_amdgcn_update_dpp(0, __float_as_int(v), 0x122, 0xf, 0xf, false)); }
;     DI void operator()(const f32x4 (&acc)[2][2][4][2], const pg8::Unit& u, int wr, int wcv, int fr, int fq) const {
;     ...
;             for (int m = 0; m < 4; ++m) {
;                 const int lrow = 64 * blk + 16 * m + fr, t = 254 * u.pm - 2 + lrow, spos = t & 2047;
;                 float o[8], r1[8], r2[8];
; #pragma unroll
;                 for (int e = 0; e < 8; ++e) { const float uc = acc[ai][0][m][e >> 2][e & 3], gv = acc[ai][1][m][e >> 2][e & 3];
;                     r1[e] = dpp_ror1(uc); r2[e] = dpp_ror2(uc);
;                     float um1 = (fr >= 1) ? r1[e] : p1[e], um2 = (fr >= 2) ? r2[e] : p2[e];
;                     if (spos < 1) um1 = 0.f;
;                     if (spos < 2) um2 = 0.f;
;                     const float v = bb[e] + w0[e] * um2 + w1[e] * um1 + w2[e] * uc;
;                     o[e] = fsilu(v) * gv; }
; #pragma unroll
;                 for (int e = 0; e < 8; ++e) { p1[e] = r1[e]; p2[e] = r2[e]; }
;                 if (lrow >= 2 && t < T) *(u32x4*)(act + (size_t)t * DFF + ch0) = pack8(o);
;             }
.LBB0_887:
	s_or_b64 exec, exec, s[58:59]
	v_add_u32_e32 v160, s53, v184
	v_cmp_gt_i32_e32 vcc, s19, v160
	v_mov_b32_dpp v143, v124 row_ror:1 row_mask:0xf bank_mask:0xf
	v_mov_b32_dpp v142, v124 row_ror:2 row_mask:0xf bank_mask:0xf
	v_mov_b32_dpp v141, v125 row_ror:1 row_mask:0xf bank_mask:0xf
	v_mov_b32_dpp v140, v125 row_ror:2 row_mask:0xf bank_mask:0xf
	v_mov_b32_dpp v139, v126 row_ror:1 row_mask:0xf bank_mask:0xf
	v_mov_b32_dpp v138, v126 row_ror:2 row_mask:0xf bank_mask:0xf
	v_mov_b32_dpp v137, v127 row_ror:1 row_mask:0xf bank_mask:0xf
	v_mov_b32_dpp v136, v127 row_ror:2 row_mask:0xf bank_mask:0xf
	v_mov_b32_dpp v135, v116 row_ror:1 row_mask:0xf bank_mask:0xf
	v_mov_b32_dpp v134, v116 row_ror:2 row_mask:0xf bank_mask:0xf
	v_mov_b32_dpp v133, v117 row_ror:1 row_mask:0xf bank_mask:0xf
	v_mov_b32_dpp v132, v117 row_ror:2 row_mask:0xf bank_mask:0xf
	v_mov_b32_dpp v131, v118 row_ror:1 row_mask:0xf bank_mask:0xf
	v_mov_b32_dpp v130, v118 row_ror:2 row_mask:0xf bank_mask:0xf
	v_mov_b32_dpp v129, v119 row_ror:1 row_mask:0xf bank_mask:0xf
	v_mov_b32_dpp v128, v119 row_ror:2 row_mask:0xf bank_mask:0xf
	s_and_b64 s[50:51], s[24:25], vcc
	s_and_saveexec_b64 s[58:59], s[50:51]
	s_cbranch_execz .LBB0_889
	v_and_b32_e32 v161, 0x7ff, v160
	v_cndmask_b32_e64 v159, v143, v159, s[40:41]
	v_cmp_eq_u32_e32 vcc, 0, v161
	v_mov_b32_e32 v164, v124
	v_cndmask_b32_e64 v124, v158, v142, s[42:43]
	v_cmp_gt_u32_e64 s[50:51], 2, v161
	v_cndmask_b32_e64 v163, v159, 0, vcc
	v_mov_b32_e32 v165, v84
	v_mov_b32_e32 v162, v88
	v_cndmask_b32_e64 v124, v124, 0, s[50:51]
	v_pk_mul_f32 v[162:163], v[164:165], v[162:163]
	v_fma_f32 v124, v80, v124, v92
	v_add_f32_e32 v124, v163, v124
	v_add_f32_e32 v161, v162, v124
	v_mul_f32_e32 v124, 0xbfb8aa3b, v161
	v_exp_f32_e32 v162, v124
	v_cndmask_b32_e64 v124, v141, v157, s[40:41]
	v_cndmask_b32_e64 v156, v156, v140, s[42:43]
	v_cndmask_b32_e64 v159, v124, 0, vcc
	v_mov_b32_e32 v124, v125
	v_mov_b32_e32 v125, v85
	v_mov_b32_e32 v158, v89
	v_cndmask_b32_e64 v156, v156, 0, s[50:51]
	v_pk_mul_f32 v[124:125], v[124:125], v[158:159]
	v_fma_f32 v156, v81, v156, v93
	v_add_f32_e32 v125, v125, v156
	v_add_f32_e32 v124, v124, v125
	v_mul_f32_e32 v125, 0xbfb8aa3b, v124
	v_exp_f32_e32 v125, v125
	v_add_f32_e32 v156, 1.0, v162
	v_rcp_f32_e32 v156, v156
	v_mov_b32_e32 v157, v86
	v_add_f32_e32 v125, 1.0, v125
	v_rcp_f32_e32 v125, v125
	v_mul_f32_e32 v156, v161, v156
	v_mul_f32_e32 v158, v120, v156
	v_mov_b32_e32 v156, v126
	v_mul_f32_e32 v120, v124, v125
	v_cndmask_b32_e64 v124, v139, v155, s[40:41]
	v_cndmask_b32_e64 v126, v154, v138, s[42:43]
	v_cndmask_b32_e64 v125, v124, 0, vcc
	v_mov_b32_e32 v124, v90
	v_cndmask_b32_e64 v126, v126, 0, s[50:51]
	v_pk_mul_f32 v[124:125], v[156:157], v[124:125]
	v_fma_f32 v126, v82, v126, v94
	v_add_f32_e32 v125, v125, v126
	v_add_f32_e32 v154, v124, v125
	v_mul_f32_e32 v124, 0xbfb8aa3b, v154
	v_exp_f32_e32 v155, v124
	v_cndmask_b32_e64 v124, v137, v153, s[40:41]
	v_cndmask_b32_e64 v125, v124, 0, vcc
	v_mov_b32_e32 v126, v127
	v_mov_b32_e32 v127, v87
	v_mov_b32_e32 v124, v91
	v_pk_mul_f32 v[124:125], v[126:127], v[124:125]
	v_cndmask_b32_e64 v126, v152, v136, s[42:43]
	v_cndmask_b32_e64 v126, v126, 0, s[50:51]
	v_fma_f32 v126, v83, v126, v95
	v_add_f32_e32 v125, v125, v126
	v_add_f32_e32 v126, v124, v125
	v_mul_f32_e32 v124, 0xbfb8aa3b, v126
	v_exp_f32_e32 v124, v124
	v_mul_f32_e32 v127, v121, v120
	v_add_f32_e32 v120, 1.0, v155
	v_rcp_f32_e32 v152, v120
	v_add_f32_e32 v120, 1.0, v124
	v_rcp_f32_e32 v153, v120
	v_cndmask_b32_e64 v120, v135, v151, s[40:41]
	v_mov_b32_e32 v124, v116
	v_cndmask_b32_e64 v116, v150, v134, s[42:43]
	v_cndmask_b32_e64 v121, v120, 0, vcc
	v_mov_b32_e32 v125, v64
	v_mov_b32_e32 v120, v68
	v_cndmask_b32_e64 v116, v116, 0, s[50:51]
	v_pk_mul_f32 v[120:121], v[124:125], v[120:121]
	v_fma_f32 v116, v60, v116, v72
	v_add_f32_e32 v116, v121, v116
	v_add_f32_e32 v124, v120, v116
	v_mul_f32_e32 v116, 0xbfb8aa3b, v124
	v_exp_f32_e32 v116, v116
	v_mul_f32_e32 v120, v154, v152
	v_mul_f32_e32 v125, v126, v153
	v_mul_f32_e32 v122, v122, v120
	v_add_f32_e32 v116, 1.0, v116
	v_rcp_f32_e32 v126, v116
	v_cndmask_b32_e64 v116, v133, v149, s[40:41]
	v_cndmask_b32_e64 v121, v116, 0, vcc
	v_mov_b32_e32 v116, v117
	v_mov_b32_e32 v117, v65
	v_mov_b32_e32 v120, v69
	v_pk_mul_f32 v[116:117], v[116:117], v[120:121]
	v_cndmask_b32_e64 v120, v148, v132, s[42:43]
	v_cndmask_b32_e64 v120, v120, 0, s[50:51]
	v_fma_f32 v120, v61, v120, v73
	v_add_f32_e32 v117, v117, v120
	v_add_f32_e32 v148, v116, v117
	v_mul_f32_e32 v116, 0xbfb8aa3b, v148
	v_exp_f32_e32 v116, v116
	v_mul_f32_e32 v117, v124, v126
	v_mul_f32_e32 v124, v112, v117
	v_mov_b32_e32 v120, v118
	v_add_f32_e32 v112, 1.0, v116
	v_cndmask_b32_e64 v116, v131, v147, s[40:41]
	v_cndmask_b32_e64 v118, v146, v130, s[42:43]
	v_cndmask_b32_e64 v117, v116, 0, vcc
	v_mov_b32_e32 v121, v66
	v_mov_b32_e32 v116, v70
	v_cndmask_b32_e64 v118, v118, 0, s[50:51]
	v_pk_mul_f32 v[116:117], v[120:121], v[116:117]
	v_fma_f32 v118, v62, v118, v74
	v_add_f32_e32 v117, v117, v118
	v_add_f32_e32 v120, v116, v117
	v_mul_f32_e32 v116, 0xbfb8aa3b, v120
	v_exp_f32_e32 v121, v116
	v_cndmask_b32_e64 v116, v129, v145, s[40:41]
	v_cndmask_b32_e64 v117, v116, 0, vcc
	v_mov_b32_e32 v118, v119
	v_mov_b32_e32 v119, v67
	v_mov_b32_e32 v116, v71
	v_pk_mul_f32 v[116:117], v[118:119], v[116:117]
	v_cndmask_b32_e64 v118, v144, v128, s[42:43]
	v_cndmask_b32_e64 v118, v118, 0, s[50:51]
	v_fma_f32 v118, v63, v118, v75
	v_add_f32_e32 v117, v117, v118
	v_add_f32_e32 v116, v116, v117
	v_mul_f32_e32 v117, 0xbfb8aa3b, v116
	v_exp_f32_e32 v117, v117
	v_rcp_f32_e32 v112, v112
	v_add_f32_e32 v118, 1.0, v121
	v_rcp_f32_e32 v118, v118
	v_add_f32_e32 v117, 1.0, v117
	v_rcp_f32_e32 v117, v117
	v_mul_f32_e32 v112, v148, v112
	v_mul_f32_e32 v119, v113, v112
	v_mul_f32_e32 v112, v120, v118
	v_mul_f32_e32 v118, v114, v112
	v_mul_f32_e32 v112, v116, v117
	v_mov_b64_e32 v[116:117], s[4:5]
	s_movk_i32 s50, 0x1600
	v_mul_f32_e32 v123, v123, v125
	v_mul_f32_e32 v115, v115, v112
	v_mad_i64_i32 v[116:117], s[50:51], v160, s50, v[116:117]
	v_cvt_pk_bf16_f32 v112, v158, v127
	v_cvt_pk_bf16_f32 v113, v122, v123
	v_cvt_pk_bf16_f32 v114, v124, v119
	v_cvt_pk_bf16_f32 v115, v118, v115
	v_lshl_add_u64 v[116:117], v[178:179], 1, v[116:117]
	global_store_dwordx4 v[116:117], v[112:115], off
; DI u32x4 pack8(const float (&f)[8]) { u32x4 w; w.x = pk2(f[0], f[1]); w.y = pk2(f[2], f[3]); w.z = pk2(f[4], f[5]); w.w = pk2(f[6], f[7]); return w; }
; DI float fsilu(float x) { return x * fsigmoid(x); }
; DI float dpp_ror1(float v) { return __int_as_float(__builtin_amdgcn_update_dpp(0, __float_as_int(v), 0x121, 0xf, 0xf, false)); }
; DI float dpp_ror2(float v) { return __int_as_float(__builtin_amdgcn_update_dpp(0, __float_as_int(v), 0x122, 0xf, 0xf, false)); }
;     DI void operator()(const f32x4 (&acc)[2][2][4][2], const pg8::Unit& u, int wr, int wcv, int fr, int fq) const {
;     ...
;             for (int m = 0; m < 4; ++m) {
;                 const int lrow = 64 * blk + 16 * m + fr, t = 254 * u.pm - 2 + lrow, spos = t & 2047;
;                 float o[8], r1[8], r2[8];
; #pragma unroll
;                 for (int e = 0; e < 8; ++e) { const float uc = acc[ai][0][m][e >> 2][e & 3], gv = acc[ai][1][m][e >> 2][e & 3];
;                     r1[e] = dpp_ror1(uc); r2[e] = dpp_ror2(uc);
;                     float um1 = (fr >= 1) ? r1[e] : p1[e], um2 = (fr >= 2) ? r2[e] : p2[e];
;                     if (spos < 1) um1 = 0.f;
;                     if (spos < 2) um2 = 0.f;
;                     const float v = bb[e] + w0[e] * um2 + w1[e] * um1 + w2[e] * uc;
;                     o[e] = fsilu(v) * gv; }
; #pragma unroll
;                 for (int e = 0; e < 8; ++e) { p1[e] = r1[e]; p2[e] = r2[e]; }
;                 if (lrow >= 2 && t < T) *(u32x4*)(act + (size_t)t * DFF + ch0) = pack8(o);
;             }
.LBB0_889:
	s_or_b64 exec, exec, s[58:59]
	s_nop 0
	v_add_u32_e32 v112, s53, v185
	v_cmp_gt_i32_e32 vcc, s19, v112
	v_mov_b32_dpp v144, v108 row_ror:1 row_mask:0xf bank_mask:0xf
	v_mov_b32_dpp v127, v108 row_ror:2 row_mask:0xf bank_mask:0xf
	v_mov_b32_dpp v126, v109 row_ror:1 row_mask:0xf bank_mask:0xf
	v_mov_b32_dpp v125, v109 row_ror:2 row_mask:0xf bank_mask:0xf
	v_mov_b32_dpp v124, v110 row_ror:1 row_mask:0xf bank_mask:0xf
	v_mov_b32_dpp v123, v110 row_ror:2 row_mask:0xf bank_mask:0xf
	v_mov_b32_dpp v122, v111 row_ror:1 row_mask:0xf bank_mask:0xf
	v_mov_b32_dpp v121, v111 row_ror:2 row_mask:0xf bank_mask:0xf
	v_mov_b32_dpp v120, v100 row_ror:1 row_mask:0xf bank_mask:0xf
	v_mov_b32_dpp v119, v100 row_ror:2 row_mask:0xf bank_mask:0xf
	v_mov_b32_dpp v118, v101 row_ror:1 row_mask:0xf bank_mask:0xf
	v_mov_b32_dpp v117, v101 row_ror:2 row_mask:0xf bank_mask:0xf
	v_mov_b32_dpp v116, v102 row_ror:1 row_mask:0xf bank_mask:0xf
	v_mov_b32_dpp v115, v102 row_ror:2 row_mask:0xf bank_mask:0xf
	v_mov_b32_dpp v114, v103 row_ror:1 row_mask:0xf bank_mask:0xf
	v_mov_b32_dpp v113, v103 row_ror:2 row_mask:0xf bank_mask:0xf
	s_and_b64 s[50:51], s[24:25], vcc
	s_and_saveexec_b64 s[58:59], s[50:51]
	s_cbranch_execz .LBB0_891
	v_and_b32_e32 v148, 0x7ff, v112
	v_cndmask_b32_e64 v143, v144, v143, s[40:41]
	v_cmp_eq_u32_e32 vcc, 0, v148
	v_mov_b32_e32 v146, v108
	v_cndmask_b32_e64 v108, v142, v127, s[42:43]
	v_cmp_gt_u32_e64 s[50:51], 2, v148
	v_cndmask_b32_e64 v145, v143, 0, vcc
	v_mov_b32_e32 v147, v84
	v_mov_b32_e32 v144, v88
	v_cndmask_b32_e64 v108, v108, 0, s[50:51]
	v_pk_mul_f32 v[144:145], v[146:147], v[144:145]
	v_fma_f32 v108, v80, v108, v92
	v_add_f32_e32 v108, v145, v108
	v_add_f32_e32 v142, v144, v108
	v_mul_f32_e32 v108, 0xbfb8aa3b, v142
	v_exp_f32_e32 v143, v108
	v_cndmask_b32_e64 v108, v126, v141, s[40:41]
	v_cndmask_b32_e64 v125, v140, v125, s[42:43]
	v_cndmask_b32_e64 v127, v108, 0, vcc
	v_mov_b32_e32 v108, v109
	v_mov_b32_e32 v109, v85
	v_mov_b32_e32 v126, v89
	v_cndmask_b32_e64 v125, v125, 0, s[50:51]
	v_pk_mul_f32 v[108:109], v[108:109], v[126:127]
	v_fma_f32 v125, v81, v125, v93
	v_add_f32_e32 v109, v109, v125
	v_add_f32_e32 v108, v108, v109
	v_mul_f32_e32 v109, 0xbfb8aa3b, v108
	v_exp_f32_e32 v109, v109
	v_add_f32_e32 v125, 1.0, v143
	v_rcp_f32_e32 v125, v125
	v_add_f32_e32 v109, 1.0, v109
	v_rcp_f32_e32 v109, v109
	v_mul_f32_e32 v125, v142, v125
	v_mul_f32_e32 v126, v104, v125
	v_mov_b32_e32 v125, v86
	v_mul_f32_e32 v104, v108, v109
	v_cndmask_b32_e64 v108, v124, v139, s[40:41]
	v_mov_b32_e32 v124, v110
	v_cndmask_b32_e64 v110, v138, v123, s[42:43]
	v_cndmask_b32_e64 v109, v108, 0, vcc
	v_mov_b32_e32 v108, v90
	v_cndmask_b32_e64 v110, v110, 0, s[50:51]
	v_pk_mul_f32 v[108:109], v[124:125], v[108:109]
	v_fma_f32 v110, v82, v110, v94
	v_add_f32_e32 v109, v109, v110
	v_add_f32_e32 v123, v108, v109
	v_mul_f32_e32 v108, 0xbfb8aa3b, v123
	v_exp_f32_e32 v124, v108
	v_cndmask_b32_e64 v108, v122, v137, s[40:41]
	v_cndmask_b32_e64 v109, v108, 0, vcc
	v_mov_b32_e32 v110, v111
	v_mov_b32_e32 v111, v87
	v_mov_b32_e32 v108, v91
	v_pk_mul_f32 v[108:109], v[110:111], v[108:109]
	v_cndmask_b32_e64 v110, v136, v121, s[42:43]
	v_cndmask_b32_e64 v110, v110, 0, s[50:51]
	v_fma_f32 v110, v83, v110, v95
	v_add_f32_e32 v109, v109, v110
	v_add_f32_e32 v110, v108, v109
	v_mul_f32_e32 v108, 0xbfb8aa3b, v110
	v_exp_f32_e32 v108, v108
	v_mul_f32_e32 v111, v105, v104
	v_add_f32_e32 v104, 1.0, v124
	v_rcp_f32_e32 v121, v104
	v_add_f32_e32 v104, 1.0, v108
	v_rcp_f32_e32 v122, v104
	v_cndmask_b32_e64 v104, v120, v135, s[40:41]
	v_mov_b32_e32 v108, v100
	v_cndmask_b32_e64 v100, v134, v119, s[42:43]
	v_cndmask_b32_e64 v105, v104, 0, vcc
	v_mov_b32_e32 v109, v64
	v_mov_b32_e32 v104, v68
	v_cndmask_b32_e64 v100, v100, 0, s[50:51]
	v_pk_mul_f32 v[104:105], v[108:109], v[104:105]
	v_fma_f32 v100, v60, v100, v72
	v_add_f32_e32 v100, v105, v100
	v_add_f32_e32 v108, v104, v100
	v_mul_f32_e32 v100, 0xbfb8aa3b, v108
	v_exp_f32_e32 v100, v100
	v_mul_f32_e32 v104, v123, v121
	v_mul_f32_e32 v109, v110, v122
	v_mul_f32_e32 v106, v106, v104
	v_add_f32_e32 v100, 1.0, v100
	v_rcp_f32_e32 v110, v100
	v_cndmask_b32_e64 v100, v118, v133, s[40:41]
	v_cndmask_b32_e64 v105, v100, 0, vcc
	v_mov_b32_e32 v100, v101
	v_mov_b32_e32 v101, v65
	v_mov_b32_e32 v104, v69
	v_pk_mul_f32 v[100:101], v[100:101], v[104:105]
	v_cndmask_b32_e64 v104, v132, v117, s[42:43]
	v_cndmask_b32_e64 v104, v104, 0, s[50:51]
	v_fma_f32 v104, v61, v104, v73
	v_add_f32_e32 v101, v101, v104
	v_add_f32_e32 v117, v100, v101
	v_mul_f32_e32 v100, 0xbfb8aa3b, v117
	v_exp_f32_e32 v100, v100
	v_mul_f32_e32 v101, v108, v110
	v_mul_f32_e32 v108, v96, v101
	v_mov_b32_e32 v104, v102
	v_add_f32_e32 v96, 1.0, v100
	v_cndmask_b32_e64 v100, v116, v131, s[40:41]
	v_cndmask_b32_e64 v102, v130, v115, s[42:43]
	v_cndmask_b32_e64 v101, v100, 0, vcc
	v_mov_b32_e32 v105, v66
	v_mov_b32_e32 v100, v70
	v_cndmask_b32_e64 v102, v102, 0, s[50:51]
	v_pk_mul_f32 v[100:101], v[104:105], v[100:101]
	v_fma_f32 v102, v62, v102, v74
	v_add_f32_e32 v101, v101, v102
	v_add_f32_e32 v104, v100, v101
	v_mul_f32_e32 v100, 0xbfb8aa3b, v104
	v_exp_f32_e32 v105, v100
	v_cndmask_b32_e64 v100, v114, v129, s[40:41]
	v_cndmask_b32_e64 v101, v100, 0, vcc
	v_mov_b32_e32 v102, v103
	v_mov_b32_e32 v103, v67
	v_mov_b32_e32 v100, v71
	v_pk_mul_f32 v[100:101], v[102:103], v[100:101]
	v_cndmask_b32_e64 v102, v128, v113, s[42:43]
	v_cndmask_b32_e64 v102, v102, 0, s[50:51]
	v_fma_f32 v102, v63, v102, v75
	v_add_f32_e32 v101, v101, v102
	v_add_f32_e32 v100, v100, v101
	v_mul_f32_e32 v101, 0xbfb8aa3b, v100
	v_exp_f32_e32 v101, v101
	v_rcp_f32_e32 v96, v96
	v_add_f32_e32 v102, 1.0, v105
	v_rcp_f32_e32 v102, v102
	v_add_f32_e32 v101, 1.0, v101
	v_rcp_f32_e32 v101, v101
	v_mul_f32_e32 v96, v117, v96
	v_mul_f32_e32 v103, v97, v96
	v_mul_f32_e32 v96, v104, v102
	v_mul_f32_e32 v102, v98, v96
	v_mul_f32_e32 v96, v100, v101
	v_mov_b64_e32 v[100:101], s[4:5]
	s_movk_i32 s50, 0x1600
	v_mul_f32_e32 v107, v107, v109
	v_mul_f32_e32 v99, v99, v96
	v_mad_i64_i32 v[100:101], s[50:51], v112, s50, v[100:101]
	v_cvt_pk_bf16_f32 v96, v126, v111
	v_cvt_pk_bf16_f32 v97, v106, v107
	v_cvt_pk_bf16_f32 v98, v108, v103
	v_cvt_pk_bf16_f32 v99, v102, v99
	v_lshl_add_u64 v[100:101], v[178:179], 1, v[100:101]
	global_store_dwordx4 v[100:101], v[96:99], off

; DI u32x4 pack8(const float (&f)[8]) { u32x4 w; w.x = pk2(f[0], f[1]); w.y = pk2(f[2], f[3]); w.z = pk2(f[4], f[5]); w.w = pk2(f[6], f[7]); return w; }
; DI float fsilu(float x) { return x * fsigmoid(x); }
; DI float dpp_ror1(float v) { return __int_as_float(__builtin_amdgcn_update_dpp(0, __float_as_int(v), 0x121, 0xf, 0xf, false)); }
; DI float dpp_ror2(float v) { return __int_as_float(__builtin_amdgcn_update_dpp(0, __float_as_int(v), 0x122, 0xf, 0xf, false)); }
;     DI void operator()(const f32x4 (&acc)[2][2][4][2], const pg8::Unit& u, int wr, int wcv, int fr, int fq) const {
;     ...
;             for (int m = 0; m < 4; ++m) {
;                 const int lrow = 64 * blk + 16 * m + fr, t = 254 * u.pm - 2 + lrow, spos = t & 2047;
;                 float o[8], r1[8], r2[8];
; #pragma unroll
;                 for (int e = 0; e < 8; ++e) { const float uc = acc[ai][0][m][e >> 2][e & 3], gv = acc[ai][1][m][e >> 2][e & 3];
;                     r1[e] = dpp_ror1(uc); r2[e] = dpp_ror2(uc);
;                     float um1 = (fr >= 1) ? r1[e] : p1[e], um2 = (fr >= 2) ? r2[e] : p2[e];
;                     if (spos < 1) um1 = 0.f;
;                     if (spos < 2) um2 = 0.f;
;                     const float v = bb[e] + w0[e] * um2 + w1[e] * um1 + w2[e] * uc;
;                     o[e] = fsilu(v) * gv; }
; #pragma unroll
;                 for (int e = 0; e < 8; ++e) { p1[e] = r1[e]; p2[e] = r2[e]; }
;                 if (lrow >= 2 && t < T) *(u32x4*)(act + (size_t)t * DFF + ch0) = pack8(o);
;             }
.LBB0_893:
	v_add_u32_e32 v122, s53, v186
	v_cmp_gt_i32_e32 vcc, s19, v122
	v_mov_b32_dpp v119, v76 row_ror:1 row_mask:0xf bank_mask:0xf
	v_mov_b32_dpp v118, v76 row_ror:2 row_mask:0xf bank_mask:0xf
	v_mov_b32_dpp v117, v77 row_ror:1 row_mask:0xf bank_mask:0xf
	v_mov_b32_dpp v116, v77 row_ror:2 row_mask:0xf bank_mask:0xf
	v_mov_b32_dpp v115, v78 row_ror:1 row_mask:0xf bank_mask:0xf
	v_mov_b32_dpp v114, v78 row_ror:2 row_mask:0xf bank_mask:0xf
	v_mov_b32_dpp v113, v79 row_ror:1 row_mask:0xf bank_mask:0xf
	v_mov_b32_dpp v112, v79 row_ror:2 row_mask:0xf bank_mask:0xf
	v_mov_b32_dpp v111, v52 row_ror:1 row_mask:0xf bank_mask:0xf
	v_mov_b32_dpp v110, v52 row_ror:2 row_mask:0xf bank_mask:0xf
	v_mov_b32_dpp v109, v53 row_ror:1 row_mask:0xf bank_mask:0xf
	v_mov_b32_dpp v108, v53 row_ror:2 row_mask:0xf bank_mask:0xf
	v_mov_b32_dpp v107, v54 row_ror:1 row_mask:0xf bank_mask:0xf
	v_mov_b32_dpp v106, v54 row_ror:2 row_mask:0xf bank_mask:0xf
	v_mov_b32_dpp v105, v55 row_ror:1 row_mask:0xf bank_mask:0xf
	v_mov_b32_dpp v104, v55 row_ror:2 row_mask:0xf bank_mask:0xf
	s_and_b64 s[50:51], s[46:47], vcc
	s_and_saveexec_b64 s[58:59], s[50:51]
	s_cbranch_execz .LBB0_895
	v_and_b32_e32 v129, 0x7ff, v122
	v_cndmask_b32_e64 v100, v119, v100, s[40:41]
	v_cmp_eq_u32_e32 vcc, 0, v129
	v_mov_b32_e32 v132, v76
	v_cndmask_b32_e64 v76, v128, v118, s[42:43]
	v_cmp_gt_u32_e64 s[50:51], 2, v129
	v_cndmask_b32_e64 v131, v100, 0, vcc
	v_mov_b32_e32 v133, v84
	v_mov_b32_e32 v130, v88
	v_cndmask_b32_e64 v76, v76, 0, s[50:51]
	v_pk_mul_f32 v[130:131], v[132:133], v[130:131]
	v_fma_f32 v76, v80, v76, v92
	v_add_f32_e32 v76, v131, v76
	v_add_f32_e32 v128, v130, v76
	v_mul_f32_e32 v76, 0xbfb8aa3b, v128
	v_exp_f32_e32 v129, v76
	v_cndmask_b32_e64 v76, v117, v101, s[40:41]
	v_cndmask_b32_e64 v101, v76, 0, vcc
	v_mov_b32_e32 v76, v77
	v_mov_b32_e32 v77, v85
	v_mov_b32_e32 v100, v89
	v_pk_mul_f32 v[76:77], v[76:77], v[100:101]
	v_cndmask_b32_e64 v100, v127, v116, s[42:43]
	v_cndmask_b32_e64 v100, v100, 0, s[50:51]
	v_fma_f32 v100, v81, v100, v93
	v_add_f32_e32 v77, v77, v100
	v_add_f32_e32 v76, v76, v77
	v_mul_f32_e32 v77, 0xbfb8aa3b, v76
	v_exp_f32_e32 v77, v77
	v_add_f32_e32 v100, 1.0, v129
	v_rcp_f32_e32 v100, v100
	v_mov_b32_e32 v101, v86
	v_add_f32_e32 v77, 1.0, v77
	v_rcp_f32_e32 v77, v77
	v_mul_f32_e32 v100, v128, v100
	v_mul_f32_e32 v127, v56, v100
	v_mov_b32_e32 v100, v78
	v_mul_f32_e32 v56, v76, v77
	v_cndmask_b32_e64 v76, v115, v102, s[40:41]
	v_cndmask_b32_e64 v78, v125, v114, s[42:43]
	v_cndmask_b32_e64 v77, v76, 0, vcc
	v_mov_b32_e32 v76, v90
	v_cndmask_b32_e64 v78, v78, 0, s[50:51]
	v_pk_mul_f32 v[76:77], v[100:101], v[76:77]
	v_fma_f32 v78, v82, v78, v94
	v_add_f32_e32 v77, v77, v78
	v_add_f32_e32 v100, v76, v77
	v_mul_f32_e32 v76, 0xbfb8aa3b, v100
	v_exp_f32_e32 v101, v76
	v_cndmask_b32_e64 v76, v113, v103, s[40:41]
	v_cndmask_b32_e64 v77, v76, 0, vcc
	v_mov_b32_e32 v78, v79
	v_mov_b32_e32 v79, v87
	v_mov_b32_e32 v76, v91
	v_pk_mul_f32 v[76:77], v[78:79], v[76:77]
	v_cndmask_b32_e64 v78, v123, v112, s[42:43]
	v_cndmask_b32_e64 v78, v78, 0, s[50:51]
	v_fma_f32 v78, v83, v78, v95
	v_add_f32_e32 v77, v77, v78
	v_add_f32_e32 v78, v76, v77
	v_mul_f32_e32 v76, 0xbfb8aa3b, v78
	v_exp_f32_e32 v76, v76
	v_mul_f32_e32 v79, v57, v56
	v_add_f32_e32 v56, 1.0, v101
	v_rcp_f32_e32 v101, v56
	v_add_f32_e32 v56, 1.0, v76
	v_rcp_f32_e32 v102, v56
	v_cndmask_b32_e64 v56, v111, v96, s[40:41]
	v_mov_b32_e32 v76, v52
	v_cndmask_b32_e64 v52, v126, v110, s[42:43]
	v_cndmask_b32_e64 v57, v56, 0, vcc
	v_mov_b32_e32 v77, v64
	v_mov_b32_e32 v56, v68
	v_cndmask_b32_e64 v52, v52, 0, s[50:51]
	v_pk_mul_f32 v[56:57], v[76:77], v[56:57]
	v_fma_f32 v52, v60, v52, v72
	v_add_f32_e32 v52, v57, v52
	v_add_f32_e32 v76, v56, v52
	v_mul_f32_e32 v52, 0xbfb8aa3b, v76
	v_exp_f32_e32 v52, v52
	v_mul_f32_e32 v56, v100, v101
	v_mul_f32_e32 v77, v78, v102
	v_mul_f32_e32 v58, v58, v56
	v_add_f32_e32 v52, 1.0, v52
	v_rcp_f32_e32 v78, v52
	v_cndmask_b32_e64 v52, v109, v97, s[40:41]
	v_cndmask_b32_e64 v57, v52, 0, vcc
	v_mov_b32_e32 v52, v53
	v_mov_b32_e32 v53, v65
	v_mov_b32_e32 v56, v69
	v_pk_mul_f32 v[52:53], v[52:53], v[56:57]
	v_cndmask_b32_e64 v56, v124, v108, s[42:43]
	v_cndmask_b32_e64 v56, v56, 0, s[50:51]
	v_fma_f32 v56, v61, v56, v73
	v_add_f32_e32 v53, v53, v56
	v_add_f32_e32 v96, v52, v53
	v_mul_f32_e32 v52, 0xbfb8aa3b, v96
	v_exp_f32_e32 v52, v52
	v_mul_f32_e32 v53, v76, v78
	v_mul_f32_e32 v76, v48, v53
	v_mov_b32_e32 v56, v54
	v_add_f32_e32 v48, 1.0, v52
	v_cndmask_b32_e64 v52, v107, v98, s[40:41]
	v_cndmask_b32_e64 v54, v121, v106, s[42:43]
	v_cndmask_b32_e64 v53, v52, 0, vcc
	v_mov_b32_e32 v57, v66
	v_mov_b32_e32 v52, v70
	v_cndmask_b32_e64 v54, v54, 0, s[50:51]
	v_pk_mul_f32 v[52:53], v[56:57], v[52:53]
	v_fma_f32 v54, v62, v54, v74
	v_add_f32_e32 v53, v53, v54
	v_add_f32_e32 v56, v52, v53
	v_mul_f32_e32 v52, 0xbfb8aa3b, v56
	v_exp_f32_e32 v57, v52
	v_cndmask_b32_e64 v52, v105, v99, s[40:41]
	v_cndmask_b32_e64 v53, v52, 0, vcc
	v_mov_b32_e32 v54, v55
	v_mov_b32_e32 v55, v67
	v_mov_b32_e32 v52, v71
	v_pk_mul_f32 v[52:53], v[54:55], v[52:53]
	v_cndmask_b32_e64 v54, v120, v104, s[42:43]
	v_cndmask_b32_e64 v54, v54, 0, s[50:51]
	v_fma_f32 v54, v63, v54, v75
	v_add_f32_e32 v53, v53, v54
	v_add_f32_e32 v52, v52, v53
	v_mul_f32_e32 v53, 0xbfb8aa3b, v52
	v_exp_f32_e32 v53, v53
	v_rcp_f32_e32 v48, v48
	v_add_f32_e32 v54, 1.0, v57
	v_rcp_f32_e32 v54, v54
	v_add_f32_e32 v53, 1.0, v53
	v_rcp_f32_e32 v53, v53
	v_mul_f32_e32 v48, v96, v48
	v_mul_f32_e32 v55, v49, v48
	v_mul_f32_e32 v48, v56, v54
	v_mul_f32_e32 v54, v50, v48
	v_mul_f32_e32 v48, v52, v53
	v_mov_b64_e32 v[52:53], s[4:5]
	s_movk_i32 s50, 0x1600
	v_mul_f32_e32 v59, v59, v77
	v_mul_f32_e32 v51, v51, v48
	v_mad_i64_i32 v[52:53], s[50:51], v122, s50, v[52:53]
	v_cvt_pk_bf16_f32 v48, v127, v79
	v_cvt_pk_bf16_f32 v49, v58, v59
	v_cvt_pk_bf16_f32 v50, v76, v55
	v_cvt_pk_bf16_f32 v51, v54, v51
	v_lshl_add_u64 v[52:53], v[178:179], 1, v[52:53]
	global_store_dwordx4 v[52:53], v[48:51], off
; DI u32x4 pack8(const float (&f)[8]) { u32x4 w; w.x = pk2(f[0], f[1]); w.y = pk2(f[2], f[3]); w.z = pk2(f[4], f[5]); w.w = pk2(f[6], f[7]); return w; }
; DI float fsilu(float x) { return x * fsigmoid(x); }
; DI float dpp_ror1(float v) { return __int_as_float(__builtin_amdgcn_update_dpp(0, __float_as_int(v), 0x121, 0xf, 0xf, false)); }
; DI float dpp_ror2(float v) { return __int_as_float(__builtin_amdgcn_update_dpp(0, __float_as_int(v), 0x122, 0xf, 0xf, false)); }
;     DI void operator()(const f32x4 (&acc)[2][2][4][2], const pg8::Unit& u, int wr, int wcv, int fr, int fq) const {
;     ...
;             for (int m = 0; m < 4; ++m) {
;                 const int lrow = 64 * blk + 16 * m + fr, t = 254 * u.pm - 2 + lrow, spos = t & 2047;
;                 float o[8], r1[8], r2[8];
; #pragma unroll
;                 for (int e = 0; e < 8; ++e) { const float uc = acc[ai][0][m][e >> 2][e & 3], gv = acc[ai][1][m][e >> 2][e & 3];
;                     r1[e] = dpp_ror1(uc); r2[e] = dpp_ror2(uc);
;                     float um1 = (fr >= 1) ? r1[e] : p1[e], um2 = (fr >= 2) ? r2[e] : p2[e];
;                     if (spos < 1) um1 = 0.f;
;                     if (spos < 2) um2 = 0.f;
;                     const float v = bb[e] + w0[e] * um2 + w1[e] * um1 + w2[e] * uc;
;                     o[e] = fsilu(v) * gv; }
; #pragma unroll
;                 for (int e = 0; e < 8; ++e) { p1[e] = r1[e]; p2[e] = r2[e]; }
;                 if (lrow >= 2 && t < T) *(u32x4*)(act + (size_t)t * DFF + ch0) = pack8(o);
;             }
.LBB0_895:
	s_or_b64 exec, exec, s[58:59]
	v_add_u32_e32 v96, s53, v187
	v_cmp_gt_i32_e32 vcc, s19, v96
	v_mov_b32_dpp v79, v44 row_ror:1 row_mask:0xf bank_mask:0xf
	v_mov_b32_dpp v78, v44 row_ror:2 row_mask:0xf bank_mask:0xf
	v_mov_b32_dpp v77, v45 row_ror:1 row_mask:0xf bank_mask:0xf
	v_mov_b32_dpp v76, v45 row_ror:2 row_mask:0xf bank_mask:0xf
	v_mov_b32_dpp v59, v46 row_ror:1 row_mask:0xf bank_mask:0xf
	v_mov_b32_dpp v58, v46 row_ror:2 row_mask:0xf bank_mask:0xf
	v_mov_b32_dpp v57, v47 row_ror:1 row_mask:0xf bank_mask:0xf
	v_mov_b32_dpp v56, v47 row_ror:2 row_mask:0xf bank_mask:0xf
	v_mov_b32_dpp v55, v36 row_ror:1 row_mask:0xf bank_mask:0xf
	v_mov_b32_dpp v54, v36 row_ror:2 row_mask:0xf bank_mask:0xf
	v_mov_b32_dpp v53, v37 row_ror:1 row_mask:0xf bank_mask:0xf
	v_mov_b32_dpp v52, v37 row_ror:2 row_mask:0xf bank_mask:0xf
	v_mov_b32_dpp v51, v38 row_ror:1 row_mask:0xf bank_mask:0xf
	v_mov_b32_dpp v50, v38 row_ror:2 row_mask:0xf bank_mask:0xf
	v_mov_b32_dpp v49, v39 row_ror:1 row_mask:0xf bank_mask:0xf
	v_mov_b32_dpp v48, v39 row_ror:2 row_mask:0xf bank_mask:0xf
	s_and_b64 s[50:51], s[34:35], vcc
	s_and_saveexec_b64 s[58:59], s[50:51]
	s_cbranch_execz .LBB0_897
	v_and_b32_e32 v97, 0x7ff, v96
	v_cndmask_b32_e64 v98, v79, v119, s[40:41]
	v_cmp_eq_u32_e32 vcc, 0, v97
	v_mov_b32_e32 v100, v44
	v_cndmask_b32_e64 v44, v118, v78, s[42:43]
	v_cmp_gt_u32_e64 s[50:51], 2, v97
	v_cndmask_b32_e64 v99, v98, 0, vcc
	v_mov_b32_e32 v101, v84
	v_mov_b32_e32 v98, v88
	v_cndmask_b32_e64 v44, v44, 0, s[50:51]
	v_pk_mul_f32 v[98:99], v[100:101], v[98:99]
	v_fma_f32 v44, v80, v44, v92
	v_add_f32_e32 v44, v99, v44
	v_add_f32_e32 v97, v98, v44
	v_mul_f32_e32 v44, 0xbfb8aa3b, v97
	v_exp_f32_e32 v100, v44
	v_cndmask_b32_e64 v44, v77, v117, s[40:41]
	v_cndmask_b32_e64 v99, v44, 0, vcc
	v_mov_b32_e32 v44, v45
	v_mov_b32_e32 v45, v85
	v_mov_b32_e32 v98, v89
	v_pk_mul_f32 v[44:45], v[44:45], v[98:99]
	v_cndmask_b32_e64 v98, v116, v76, s[42:43]
	v_cndmask_b32_e64 v98, v98, 0, s[50:51]
	v_fma_f32 v98, v81, v98, v93
	v_add_f32_e32 v45, v45, v98
	v_add_f32_e32 v44, v44, v45
	v_mul_f32_e32 v45, 0xbfb8aa3b, v44
	v_exp_f32_e32 v45, v45
	v_add_f32_e32 v98, 1.0, v100
	v_rcp_f32_e32 v98, v98
	v_mov_b32_e32 v99, v86
	v_add_f32_e32 v45, 1.0, v45
	v_rcp_f32_e32 v45, v45
	v_mul_f32_e32 v97, v97, v98
	v_mul_f32_e32 v97, v40, v97
	v_mov_b32_e32 v98, v46
	v_mul_f32_e32 v40, v44, v45
	v_cndmask_b32_e64 v44, v59, v115, s[40:41]
	v_cndmask_b32_e64 v46, v114, v58, s[42:43]
	v_cndmask_b32_e64 v45, v44, 0, vcc
	v_mov_b32_e32 v44, v90
	v_cndmask_b32_e64 v46, v46, 0, s[50:51]
	v_pk_mul_f32 v[44:45], v[98:99], v[44:45]
	v_fma_f32 v46, v82, v46, v94
	v_add_f32_e32 v45, v45, v46
	v_add_f32_e32 v98, v44, v45
	v_mul_f32_e32 v44, 0xbfb8aa3b, v98
	v_exp_f32_e32 v99, v44
	v_cndmask_b32_e64 v44, v57, v113, s[40:41]
	v_cndmask_b32_e64 v45, v44, 0, vcc
	v_mov_b32_e32 v46, v47
	v_mov_b32_e32 v47, v87
	v_mov_b32_e32 v44, v91
	v_pk_mul_f32 v[44:45], v[46:47], v[44:45]
	v_cndmask_b32_e64 v46, v112, v56, s[42:43]
	v_cndmask_b32_e64 v46, v46, 0, s[50:51]
	v_fma_f32 v46, v83, v46, v95
	v_add_f32_e32 v45, v45, v46
	v_add_f32_e32 v46, v44, v45
	v_mul_f32_e32 v44, 0xbfb8aa3b, v46
	v_exp_f32_e32 v44, v44
	v_mul_f32_e32 v47, v41, v40
	v_add_f32_e32 v40, 1.0, v99
	v_rcp_f32_e32 v99, v40
	v_add_f32_e32 v40, 1.0, v44
	v_rcp_f32_e32 v100, v40
	v_cndmask_b32_e64 v40, v55, v111, s[40:41]
	v_mov_b32_e32 v44, v36
	v_cndmask_b32_e64 v36, v110, v54, s[42:43]
	v_cndmask_b32_e64 v41, v40, 0, vcc
	v_mov_b32_e32 v45, v64
	v_mov_b32_e32 v40, v68
	v_cndmask_b32_e64 v36, v36, 0, s[50:51]
	v_pk_mul_f32 v[40:41], v[44:45], v[40:41]
	v_fma_f32 v36, v60, v36, v72
	v_add_f32_e32 v36, v41, v36
	v_add_f32_e32 v44, v40, v36
	v_mul_f32_e32 v36, 0xbfb8aa3b, v44
	v_exp_f32_e32 v36, v36
	v_mul_f32_e32 v40, v98, v99
	v_mul_f32_e32 v45, v46, v100
	v_mul_f32_e32 v42, v42, v40
	v_add_f32_e32 v36, 1.0, v36
	v_rcp_f32_e32 v46, v36
	v_cndmask_b32_e64 v36, v53, v109, s[40:41]
	v_cndmask_b32_e64 v41, v36, 0, vcc
	v_mov_b32_e32 v36, v37
	v_mov_b32_e32 v37, v65
	v_mov_b32_e32 v40, v69
	v_pk_mul_f32 v[36:37], v[36:37], v[40:41]
	v_cndmask_b32_e64 v40, v108, v52, s[42:43]
	v_cndmask_b32_e64 v40, v40, 0, s[50:51]
	v_fma_f32 v40, v61, v40, v73
	v_add_f32_e32 v37, v37, v40
	v_add_f32_e32 v98, v36, v37
	v_mul_f32_e32 v36, 0xbfb8aa3b, v98
	v_exp_f32_e32 v36, v36
	v_mul_f32_e32 v37, v44, v46
	v_mul_f32_e32 v44, v32, v37
	v_mov_b32_e32 v40, v38
	v_add_f32_e32 v32, 1.0, v36
	v_cndmask_b32_e64 v36, v51, v107, s[40:41]
	v_cndmask_b32_e64 v38, v106, v50, s[42:43]
	v_cndmask_b32_e64 v37, v36, 0, vcc
	v_mov_b32_e32 v41, v66
	v_mov_b32_e32 v36, v70
	v_cndmask_b32_e64 v38, v38, 0, s[50:51]
	v_pk_mul_f32 v[36:37], v[40:41], v[36:37]
	v_fma_f32 v38, v62, v38, v74
	v_add_f32_e32 v37, v37, v38
	v_add_f32_e32 v40, v36, v37
	v_mul_f32_e32 v36, 0xbfb8aa3b, v40
	v_exp_f32_e32 v41, v36
	v_cndmask_b32_e64 v36, v49, v105, s[40:41]
	v_cndmask_b32_e64 v37, v36, 0, vcc
	v_mov_b32_e32 v38, v39
	v_mov_b32_e32 v39, v67
	v_mov_b32_e32 v36, v71
	v_pk_mul_f32 v[36:37], v[38:39], v[36:37]
	v_cndmask_b32_e64 v38, v104, v48, s[42:43]
	v_cndmask_b32_e64 v38, v38, 0, s[50:51]
	v_fma_f32 v38, v63, v38, v75
	v_add_f32_e32 v37, v37, v38
	v_add_f32_e32 v36, v36, v37
	v_mul_f32_e32 v37, 0xbfb8aa3b, v36
	v_exp_f32_e32 v37, v37
	v_rcp_f32_e32 v32, v32
	v_add_f32_e32 v38, 1.0, v41
	v_rcp_f32_e32 v38, v38
	v_add_f32_e32 v37, 1.0, v37
	v_rcp_f32_e32 v37, v37
	v_mul_f32_e32 v32, v98, v32
	v_mul_f32_e32 v39, v33, v32
	v_mul_f32_e32 v32, v40, v38
	v_mul_f32_e32 v38, v34, v32
	v_mul_f32_e32 v32, v36, v37
	v_mov_b64_e32 v[36:37], s[4:5]
	s_movk_i32 s50, 0x1600
	v_mul_f32_e32 v43, v43, v45
	v_mul_f32_e32 v35, v35, v32
	v_mad_i64_i32 v[36:37], s[50:51], v96, s50, v[36:37]
	v_cvt_pk_bf16_f32 v32, v97, v47
	v_cvt_pk_bf16_f32 v33, v42, v43
	v_cvt_pk_bf16_f32 v34, v44, v39
	v_cvt_pk_bf16_f32 v35, v38, v35
	v_lshl_add_u64 v[36:37], v[178:179], 1, v[36:37]
	global_store_dwordx4 v[36:37], v[32:35], off
; DI u32x4 pack8(const float (&f)[8]) { u32x4 w; w.x = pk2(f[0], f[1]); w.y = pk2(f[2], f[3]); w.z = pk2(f[4], f[5]); w.w = pk2(f[6], f[7]); return w; }
; DI float fsilu(float x) { return x * fsigmoid(x); }
; DI float dpp_ror1(float v) { return __int_as_float(__builtin_amdgcn_update_dpp(0, __float_as_int(v), 0x121, 0xf, 0xf, false)); }
; DI float dpp_ror2(float v) { return __int_as_float(__builtin_amdgcn_update_dpp(0, __float_as_int(v), 0x122, 0xf, 0xf, false)); }
;     DI void operator()(const f32x4 (&acc)[2][2][4][2], const pg8::Unit& u, int wr, int wcv, int fr, int fq) const {
;     ...
;             for (int m = 0; m < 4; ++m) {
;                 const int lrow = 64 * blk + 16 * m + fr, t = 254 * u.pm - 2 + lrow, spos = t & 2047;
;                 float o[8], r1[8], r2[8];
; #pragma unroll
;                 for (int e = 0; e < 8; ++e) { const float uc = acc[ai][0][m][e >> 2][e & 3], gv = acc[ai][1][m][e >> 2][e & 3];
;                     r1[e] = dpp_ror1(uc); r2[e] = dpp_ror2(uc);
;                     float um1 = (fr >= 1) ? r1[e] : p1[e], um2 = (fr >= 2) ? r2[e] : p2[e];
;                     if (spos < 1) um1 = 0.f;
;                     if (spos < 2) um2 = 0.f;
;                     const float v = bb[e] + w0[e] * um2 + w1[e] * um1 + w2[e] * uc;
;                     o[e] = fsilu(v) * gv; }
; #pragma unroll
;                 for (int e = 0; e < 8; ++e) { p1[e] = r1[e]; p2[e] = r2[e]; }
;                 if (lrow >= 2 && t < T) *(u32x4*)(act + (size_t)t * DFF + ch0) = pack8(o);
;             }
.LBB0_897:
	s_or_b64 exec, exec, s[58:59]
	v_add_u32_e32 v96, s53, v188
	v_cmp_gt_i32_e32 vcc, s19, v96
	v_mov_b32_dpp v46, v28 row_ror:1 row_mask:0xf bank_mask:0xf
	v_mov_b32_dpp v44, v28 row_ror:2 row_mask:0xf bank_mask:0xf
	v_mov_b32_dpp v47, v29 row_ror:1 row_mask:0xf bank_mask:0xf
	v_mov_b32_dpp v45, v29 row_ror:2 row_mask:0xf bank_mask:0xf
	v_mov_b32_dpp v42, v30 row_ror:1 row_mask:0xf bank_mask:0xf
	v_mov_b32_dpp v40, v30 row_ror:2 row_mask:0xf bank_mask:0xf
	v_mov_b32_dpp v43, v31 row_ror:1 row_mask:0xf bank_mask:0xf
	v_mov_b32_dpp v41, v31 row_ror:2 row_mask:0xf bank_mask:0xf
	v_mov_b32_dpp v38, v20 row_ror:1 row_mask:0xf bank_mask:0xf
	v_mov_b32_dpp v36, v20 row_ror:2 row_mask:0xf bank_mask:0xf
	v_mov_b32_dpp v39, v21 row_ror:1 row_mask:0xf bank_mask:0xf
	v_mov_b32_dpp v37, v21 row_ror:2 row_mask:0xf bank_mask:0xf
	v_mov_b32_dpp v34, v22 row_ror:1 row_mask:0xf bank_mask:0xf
	v_mov_b32_dpp v32, v22 row_ror:2 row_mask:0xf bank_mask:0xf
	v_mov_b32_dpp v35, v23 row_ror:1 row_mask:0xf bank_mask:0xf
	v_mov_b32_dpp v33, v23 row_ror:2 row_mask:0xf bank_mask:0xf
	s_and_b64 s[50:51], s[34:35], vcc
	s_and_saveexec_b64 s[58:59], s[50:51]
	s_cbranch_execz .LBB0_899
	v_and_b32_e32 v97, 0x7ff, v96
	v_cndmask_b32_e64 v79, v46, v79, s[40:41]
	v_cmp_eq_u32_e32 vcc, 0, v97
	v_mov_b32_e32 v100, v28
	v_cndmask_b32_e64 v28, v78, v44, s[42:43]
	v_cmp_gt_u32_e64 s[50:51], 2, v97
	v_cndmask_b32_e64 v99, v79, 0, vcc
	v_mov_b32_e32 v101, v84
	v_mov_b32_e32 v98, v88
	v_cndmask_b32_e64 v28, v28, 0, s[50:51]
	v_pk_mul_f32 v[98:99], v[100:101], v[98:99]
	v_fma_f32 v28, v80, v28, v92
	v_add_f32_e32 v28, v99, v28
	v_add_f32_e32 v97, v98, v28
	v_mul_f32_e32 v28, 0xbfb8aa3b, v97
	v_exp_f32_e32 v98, v28
	v_cndmask_b32_e64 v28, v47, v77, s[40:41]
	v_cndmask_b32_e64 v76, v76, v45, s[42:43]
	v_cndmask_b32_e64 v79, v28, 0, vcc
	v_mov_b32_e32 v28, v29
	v_mov_b32_e32 v29, v85
	v_mov_b32_e32 v78, v89
	v_cndmask_b32_e64 v76, v76, 0, s[50:51]
	v_pk_mul_f32 v[28:29], v[28:29], v[78:79]
	v_fma_f32 v76, v81, v76, v93
	v_add_f32_e32 v29, v29, v76
	v_add_f32_e32 v28, v28, v29
	v_mul_f32_e32 v29, 0xbfb8aa3b, v28
	v_exp_f32_e32 v29, v29
	v_add_f32_e32 v76, 1.0, v98
	v_rcp_f32_e32 v76, v76
	v_mov_b32_e32 v77, v86
	v_add_f32_e32 v29, 1.0, v29
	v_rcp_f32_e32 v29, v29
	v_mul_f32_e32 v76, v97, v76
	v_mul_f32_e32 v78, v24, v76
	v_mov_b32_e32 v76, v30
	v_mul_f32_e32 v24, v28, v29
	v_cndmask_b32_e64 v28, v42, v59, s[40:41]
	v_cndmask_b32_e64 v30, v58, v40, s[42:43]
	v_cndmask_b32_e64 v29, v28, 0, vcc
	v_mov_b32_e32 v28, v90
	v_cndmask_b32_e64 v30, v30, 0, s[50:51]
	v_pk_mul_f32 v[28:29], v[76:77], v[28:29]
	v_fma_f32 v30, v82, v30, v94
	v_add_f32_e32 v29, v29, v30
	v_add_f32_e32 v58, v28, v29
	v_mul_f32_e32 v28, 0xbfb8aa3b, v58
	v_exp_f32_e32 v59, v28
	v_cndmask_b32_e64 v28, v43, v57, s[40:41]
	v_cndmask_b32_e64 v29, v28, 0, vcc
	v_mov_b32_e32 v30, v31
	v_mov_b32_e32 v31, v87
	v_mov_b32_e32 v28, v91
	v_pk_mul_f32 v[28:29], v[30:31], v[28:29]
	v_cndmask_b32_e64 v30, v56, v41, s[42:43]
	v_cndmask_b32_e64 v30, v30, 0, s[50:51]
	v_fma_f32 v30, v83, v30, v95
	v_add_f32_e32 v29, v29, v30
	v_add_f32_e32 v30, v28, v29
	v_mul_f32_e32 v28, 0xbfb8aa3b, v30
	v_exp_f32_e32 v28, v28
	v_mul_f32_e32 v31, v25, v24
	v_add_f32_e32 v24, 1.0, v59
	v_rcp_f32_e32 v56, v24
	v_add_f32_e32 v24, 1.0, v28
	v_rcp_f32_e32 v57, v24
	v_cndmask_b32_e64 v24, v38, v55, s[40:41]
	v_mov_b32_e32 v28, v20
	v_cndmask_b32_e64 v20, v54, v36, s[42:43]
	v_cndmask_b32_e64 v25, v24, 0, vcc
	v_mov_b32_e32 v29, v64
	v_mov_b32_e32 v24, v68
	v_cndmask_b32_e64 v20, v20, 0, s[50:51]
	v_pk_mul_f32 v[24:25], v[28:29], v[24:25]
	v_fma_f32 v20, v60, v20, v72
	v_add_f32_e32 v20, v25, v20
	v_add_f32_e32 v28, v24, v20
	v_mul_f32_e32 v20, 0xbfb8aa3b, v28
	v_exp_f32_e32 v20, v20
	v_mul_f32_e32 v24, v58, v56
	v_mul_f32_e32 v29, v30, v57
	v_mul_f32_e32 v26, v26, v24
	v_add_f32_e32 v20, 1.0, v20
	v_rcp_f32_e32 v30, v20
	v_cndmask_b32_e64 v20, v39, v53, s[40:41]
	v_cndmask_b32_e64 v25, v20, 0, vcc
	v_mov_b32_e32 v20, v21
	v_mov_b32_e32 v21, v65
	v_mov_b32_e32 v24, v69
	v_pk_mul_f32 v[20:21], v[20:21], v[24:25]
	v_cndmask_b32_e64 v24, v52, v37, s[42:43]
	v_cndmask_b32_e64 v24, v24, 0, s[50:51]
	v_fma_f32 v24, v61, v24, v73
	v_add_f32_e32 v21, v21, v24
	v_add_f32_e32 v52, v20, v21
	v_mul_f32_e32 v20, 0xbfb8aa3b, v52
	v_exp_f32_e32 v20, v20
	v_mul_f32_e32 v21, v28, v30
	v_mul_f32_e32 v28, v16, v21
	v_mov_b32_e32 v24, v22
	v_add_f32_e32 v16, 1.0, v20
	v_cndmask_b32_e64 v20, v34, v51, s[40:41]
	v_cndmask_b32_e64 v22, v50, v32, s[42:43]
	v_cndmask_b32_e64 v21, v20, 0, vcc
	v_mov_b32_e32 v25, v66
	v_mov_b32_e32 v20, v70
	v_cndmask_b32_e64 v22, v22, 0, s[50:51]
	v_pk_mul_f32 v[20:21], v[24:25], v[20:21]
	v_fma_f32 v22, v62, v22, v74
	v_add_f32_e32 v21, v21, v22
	v_add_f32_e32 v24, v20, v21
	v_mul_f32_e32 v20, 0xbfb8aa3b, v24
	v_exp_f32_e32 v25, v20
	v_cndmask_b32_e64 v20, v35, v49, s[40:41]
	v_cndmask_b32_e64 v21, v20, 0, vcc
	v_mov_b32_e32 v22, v23
	v_mov_b32_e32 v23, v67
	v_mov_b32_e32 v20, v71
	v_pk_mul_f32 v[20:21], v[22:23], v[20:21]
	v_cndmask_b32_e64 v22, v48, v33, s[42:43]
	v_cndmask_b32_e64 v22, v22, 0, s[50:51]
	v_fma_f32 v22, v63, v22, v75
	v_add_f32_e32 v21, v21, v22
	v_add_f32_e32 v20, v20, v21
	v_mul_f32_e32 v21, 0xbfb8aa3b, v20
	v_exp_f32_e32 v21, v21
	v_rcp_f32_e32 v16, v16
	v_add_f32_e32 v22, 1.0, v25
	v_rcp_f32_e32 v22, v22
	v_add_f32_e32 v21, 1.0, v21
	v_rcp_f32_e32 v21, v21
	v_mul_f32_e32 v16, v52, v16
	v_mul_f32_e32 v23, v17, v16
	v_mul_f32_e32 v16, v24, v22
	v_mul_f32_e32 v22, v18, v16
	v_mul_f32_e32 v16, v20, v21
	v_mov_b64_e32 v[20:21], s[4:5]
	s_movk_i32 s50, 0x1600
	v_mul_f32_e32 v27, v27, v29
	v_mul_f32_e32 v19, v19, v16
	v_mad_i64_i32 v[20:21], s[50:51], v96, s50, v[20:21]
	v_cvt_pk_bf16_f32 v16, v78, v31
	v_cvt_pk_bf16_f32 v17, v26, v27
	v_cvt_pk_bf16_f32 v18, v28, v23
	v_cvt_pk_bf16_f32 v19, v22, v19
	v_lshl_add_u64 v[20:21], v[178:179], 1, v[20:21]
	global_store_dwordx4 v[20:21], v[16:19], off
; DI u32x4 pack8(const float (&f)[8]) { u32x4 w; w.x = pk2(f[0], f[1]); w.y = pk2(f[2], f[3]); w.z = pk2(f[4], f[5]); w.w = pk2(f[6], f[7]); return w; }
; DI float fsilu(float x) { return x * fsigmoid(x); }
; DI float dpp_ror1(float v) { return __int_as_float(__builtin_amdgcn_update_dpp(0, __float_as_int(v), 0x121, 0xf, 0xf, false)); }
; DI float dpp_ror2(float v) { return __int_as_float(__builtin_amdgcn_update_dpp(0, __float_as_int(v), 0x122, 0xf, 0xf, false)); }
;     DI void operator()(const f32x4 (&acc)[2][2][4][2], const pg8::Unit& u, int wr, int wcv, int fr, int fq) const {
;     ...
;             for (int m = 0; m < 4; ++m) {
;                 const int lrow = 64 * blk + 16 * m + fr, t = 254 * u.pm - 2 + lrow, spos = t & 2047;
;                 float o[8], r1[8], r2[8];
; #pragma unroll
;                 for (int e = 0; e < 8; ++e) { const float uc = acc[ai][0][m][e >> 2][e & 3], gv = acc[ai][1][m][e >> 2][e & 3];
;                     r1[e] = dpp_ror1(uc); r2[e] = dpp_ror2(uc);
;                     float um1 = (fr >= 1) ? r1[e] : p1[e], um2 = (fr >= 2) ? r2[e] : p2[e];
;                     if (spos < 1) um1 = 0.f;
;                     if (spos < 2) um2 = 0.f;
;                     const float v = bb[e] + w0[e] * um2 + w1[e] * um1 + w2[e] * uc;
;                     o[e] = fsilu(v) * gv; }
; #pragma unroll
;                 for (int e = 0; e < 8; ++e) { p1[e] = r1[e]; p2[e] = r2[e]; }
;                 if (lrow >= 2 && t < T) *(u32x4*)(act + (size_t)t * DFF + ch0) = pack8(o);
.LBB0_899:
	s_or_b64 exec, exec, s[58:59]
	s_nop 0
	v_add_u32_e32 v16, s53, v189
	v_cmp_gt_i32_e32 vcc, s19, v16
	v_mov_b32_dpp v31, v12 row_ror:1 row_mask:0xf bank_mask:0xf
	v_mov_b32_dpp v29, v12 row_ror:2 row_mask:0xf bank_mask:0xf
	v_mov_b32_dpp v48, v13 row_ror:1 row_mask:0xf bank_mask:0xf
	v_mov_b32_dpp v30, v13 row_ror:2 row_mask:0xf bank_mask:0xf
	v_mov_b32_dpp v27, v14 row_ror:1 row_mask:0xf bank_mask:0xf
	v_mov_b32_dpp v25, v14 row_ror:2 row_mask:0xf bank_mask:0xf
	v_mov_b32_dpp v28, v15 row_ror:1 row_mask:0xf bank_mask:0xf
	v_mov_b32_dpp v26, v15 row_ror:2 row_mask:0xf bank_mask:0xf
	v_mov_b32_dpp v23, v4 row_ror:1 row_mask:0xf bank_mask:0xf
	v_mov_b32_dpp v21, v4 row_ror:2 row_mask:0xf bank_mask:0xf
	v_mov_b32_dpp v24, v5 row_ror:1 row_mask:0xf bank_mask:0xf
	v_mov_b32_dpp v22, v5 row_ror:2 row_mask:0xf bank_mask:0xf
	v_mov_b32_dpp v19, v6 row_ror:1 row_mask:0xf bank_mask:0xf
	v_mov_b32_dpp v17, v6 row_ror:2 row_mask:0xf bank_mask:0xf
	v_mov_b32_dpp v20, v7 row_ror:1 row_mask:0xf bank_mask:0xf
	v_mov_b32_dpp v18, v7 row_ror:2 row_mask:0xf bank_mask:0xf
	s_and_b64 s[50:51], s[34:35], vcc
	s_and_saveexec_b64 s[58:59], s[50:51]
	s_cbranch_execz .LBB0_901
	v_and_b32_e32 v49, 0x7ff, v16
	v_cmp_eq_u32_e64 s[50:51], 0, v49
	v_cmp_gt_u32_e32 vcc, 2, v49
	v_cndmask_b32_e64 v31, v31, v46, s[40:41]
	v_cndmask_b32_e64 v46, v48, v47, s[40:41]
	v_cndmask_b32_e64 v29, v44, v29, s[42:43]
	v_cndmask_b32_e64 v30, v45, v30, s[42:43]
	v_cndmask_b32_e64 v47, v46, 0, s[50:51]
	v_cndmask_b32_e64 v46, v31, 0, s[50:51]
	v_cndmask_b32_e64 v31, v30, 0, vcc
	v_cndmask_b32_e64 v30, v29, 0, vcc
	v_pk_fma_f32 v[30:31], v[80:81], v[30:31], v[92:93]
	v_cndmask_b32_e64 v25, v40, v25, s[42:43]
	v_pk_fma_f32 v[30:31], v[84:85], v[46:47], v[30:31]
	v_cndmask_b32_e64 v26, v41, v26, s[42:43]
	v_pk_fma_f32 v[12:13], v[12:13], v[88:89], v[30:31]
	s_nop 0
	v_mul_f32_e32 v29, 0xbfb8aa3b, v12
	v_exp_f32_e32 v29, v29
	s_nop 0
	v_add_f32_e32 v29, 1.0, v29
	v_rcp_f32_e32 v30, v29
	v_mul_f32_e32 v29, 0xbfb8aa3b, v13
	v_exp_f32_e32 v29, v29
	s_nop 0
	v_add_f32_e32 v29, 1.0, v29
	v_rcp_f32_e32 v31, v29
	s_nop 0
	v_pk_mul_f32 v[12:13], v[12:13], v[30:31]
	s_nop 0
	v_pk_mul_f32 v[8:9], v[8:9], v[12:13]
	v_cndmask_b32_e64 v12, v27, v42, s[40:41]
	v_cndmask_b32_e64 v13, v28, v43, s[40:41]
	v_cndmask_b32_e64 v27, v26, 0, vcc
	v_cndmask_b32_e64 v26, v25, 0, vcc
	v_cndmask_b32_e64 v13, v13, 0, s[50:51]
	v_cndmask_b32_e64 v12, v12, 0, s[50:51]
	v_pk_fma_f32 v[26:27], v[82:83], v[26:27], v[94:95]
	s_nop 0
	v_pk_fma_f32 v[12:13], v[86:87], v[12:13], v[26:27]
	s_nop 0
	v_pk_fma_f32 v[12:13], v[14:15], v[90:91], v[12:13]
	s_nop 0
	v_mul_f32_e32 v14, 0xbfb8aa3b, v12
	v_mul_f32_e32 v15, 0xbfb8aa3b, v13
	v_exp_f32_e32 v14, v14
	v_exp_f32_e32 v15, v15
	v_add_f32_e32 v14, 1.0, v14
	v_add_f32_e32 v15, 1.0, v15
	v_rcp_f32_e32 v14, v14
	v_rcp_f32_e32 v15, v15
	s_nop 0
	v_pk_mul_f32 v[12:13], v[12:13], v[14:15]
	v_cndmask_b32_e64 v14, v36, v21, s[42:43]
	v_cndmask_b32_e64 v15, v37, v22, s[42:43]
	v_pk_mul_f32 v[10:11], v[10:11], v[12:13]
	v_cndmask_b32_e64 v12, v23, v38, s[40:41]
	v_cndmask_b32_e64 v13, v24, v39, s[40:41]
	v_cndmask_b32_e64 v15, v15, 0, vcc
	v_cndmask_b32_e64 v14, v14, 0, vcc
	v_cndmask_b32_e64 v13, v13, 0, s[50:51]
	v_cndmask_b32_e64 v12, v12, 0, s[50:51]
	v_pk_fma_f32 v[14:15], v[60:61], v[14:15], v[72:73]
	s_nop 0
	v_pk_fma_f32 v[12:13], v[64:65], v[12:13], v[14:15]
	s_nop 0
	v_pk_fma_f32 v[4:5], v[4:5], v[68:69], v[12:13]
	s_nop 0
	v_mul_f32_e32 v12, 0xbfb8aa3b, v4
	v_mul_f32_e32 v13, 0xbfb8aa3b, v5
	v_exp_f32_e32 v12, v12
	v_exp_f32_e32 v13, v13
	v_add_f32_e32 v12, 1.0, v12
	v_add_f32_e32 v13, 1.0, v13
	v_rcp_f32_e32 v12, v12
	v_rcp_f32_e32 v13, v13
	s_nop 0
	v_pk_mul_f32 v[4:5], v[4:5], v[12:13]
	v_cndmask_b32_e64 v12, v32, v17, s[42:43]
	v_cndmask_b32_e64 v13, v33, v18, s[42:43]
	v_pk_mul_f32 v[4:5], v[0:1], v[4:5]
	v_cndmask_b32_e64 v0, v19, v34, s[40:41]
	v_cndmask_b32_e64 v1, v20, v35, s[40:41]
	v_cndmask_b32_e64 v13, v13, 0, vcc
	v_cndmask_b32_e64 v12, v12, 0, vcc
	v_cndmask_b32_e64 v1, v1, 0, s[50:51]
	v_cndmask_b32_e64 v0, v0, 0, s[50:51]
	v_pk_fma_f32 v[12:13], v[62:63], v[12:13], v[74:75]
	s_movk_i32 s50, 0x1600
	v_pk_fma_f32 v[0:1], v[66:67], v[0:1], v[12:13]
	s_nop 0
	v_pk_fma_f32 v[0:1], v[6:7], v[70:71], v[0:1]
	s_nop 0
	v_mul_f32_e32 v6, 0xbfb8aa3b, v0
	v_mul_f32_e32 v7, 0xbfb8aa3b, v1
	v_exp_f32_e32 v6, v6
	v_exp_f32_e32 v7, v7
	v_add_f32_e32 v6, 1.0, v6
	v_add_f32_e32 v7, 1.0, v7
	v_rcp_f32_e32 v6, v6
	v_rcp_f32_e32 v7, v7
	s_nop 0
	v_pk_mul_f32 v[0:1], v[0:1], v[6:7]
	s_nop 0
	v_pk_mul_f32 v[6:7], v[2:3], v[0:1]
	v_cvt_pk_bf16_f32 v2, v4, v5
	v_mov_b64_e32 v[4:5], s[4:5]
	v_mad_i64_i32 v[4:5], s[50:51], v16, s50, v[4:5]
	v_cvt_pk_bf16_f32 v0, v8, v9
	v_cvt_pk_bf16_f32 v1, v10, v11
	v_cvt_pk_bf16_f32 v3, v6, v7
	v_lshl_add_u64 v[4:5], v[178:179], 1, v[4:5]
	global_store_dwordx4 v[4:5], v[0:3], off
